# EpiResid front: first four residual loads (row block m=0) issued before the vector wait (vmcnt 4), multiplies after
# baseline (speedup 1.0000x reference)
;     __device__ __forceinline__ void operator()(const f32x4 (&acc)[2][2][4][2], const Unit& u, int wr, int wc, int fr, int fq) const {
;         const int b = (u.pm * BM) >> 11; const float cf_ = coef;
;         const int colb = u.pn * BM + wc * 32 + fq * 4;
;         f32x4 gvv[2][2], gsv[2][2], rgv[2][2];
; #pragma unroll
;         for (int bj = 0; bj < 2; ++bj)
; #pragma unroll
;             for (int n = 0; n < 2; ++n) { const f32x4 t_ = *(const f32x4*)(modp + (size_t)b * 9216 + colb + bj * HALF + n * 16); gvv[bj][n] = (f32x4){t_[0] * cf_, t_[1] * cf_, t_[2] * cf_, t_[3] * cf_};
;                 if (HAS_AN) gsv[bj][n] = *(const f32x4*)(gs + (size_t)b * 1024 + colb + bj * HALF + n * 16);
;                 if (!FROM_F32) rgv[bj][n] = *(const f32x4*)(rgs + (size_t)b * 1024 + colb + bj * HALF + n * 16); }
;         const size_t rowoff = (size_t)(u.pm * BM + wr * 64 + fr) * DM + colb;
;         const float* __restrict__ basep = xp + rowoff;
;         float* __restrict__ outp = X + rowoff;
;         bf16_t* anp = An + rowoff;
;         float* ssqp = ssq + u.pm * BM + wr * 64 + fr;
; #pragma unroll
;         for (int ai = 0; ai < 2; ++ai) {
;             f32x4 bsf[FROM_F32 ? 2 : 1][2][2]; u32x2 bsh[FROM_F32 ? 1 : 4][2][2];
;             if (!FROM_F32) {
; #pragma unroll
;                 for (int m = 0; m < 4; ++m)
; #pragma unroll
;                     for (int bj = 0; bj < 2; ++bj)
; #pragma unroll
;                         for (int n = 0; n < 2; ++n) bsh[m][bj][n] = *(const u32x2*)(anp + (size_t)(ai * HALF + m * 16) * DM + bj * HALF + n * 16);
;             }
; #pragma unroll
;             for (int mp = 0; mp < 2; ++mp) {
;                 if (FROM_F32) {
; #pragma unroll
;                     for (int mm = 0; mm < 2; ++mm)
; #pragma unroll
;                         for (int bj = 0; bj < 2; ++bj)
; #pragma unroll
;                             for (int n = 0; n < 2; ++n) bsf[mm][bj][n] = *(const f32x4*)(basep + (size_t)(ai * HALF + (2 * mp + mm) * 16) * DM + bj * HALF + n * 16);
;                 }
; #pragma unroll
;                 for (int mm = 0; mm < 2; ++mm) {
;                     const int m = 2 * mp + mm; const size_t ro = (size_t)(ai * HALF + m * 16) * DM; float sq = 0.f;
; #pragma unroll
;                     for (int bj = 0; bj < 2; ++bj)
; #pragma unroll
;                         for (int n = 0; n < 2; ++n) {
.LBB0_363:
	s_ashr_i32 s20, s97, 3
	v_lshl_or_b32 v186, s17, 8, v181
	s_ashr_i32 s21, s20, 31
	s_mul_i32 s28, s20, 0x9000
	s_mul_hi_i32 s17, s20, 0x9000
	s_add_u32 s28, s36, s28
	v_ashrrev_i32_e32 v187, 31, v186
	s_addc_u32 s29, s37, s17
	v_lshlrev_b64 v[60:61], 2, v[186:187]
	s_lshl_b64 s[20:21], s[20:21], 12
	v_lshl_add_u64 v[72:73], s[28:29], 0, v[60:61]
	s_add_u32 s28, s38, s20
	s_addc_u32 s29, s39, s21
	s_add_u32 s20, s34, s20
	s_addc_u32 s21, s35, s21
	v_lshl_add_u64 v[74:75], s[28:29], 0, v[60:61]
	v_lshl_add_u64 v[204:205], s[20:21], 0, v[60:61]
	global_load_dwordx4 v[208:211], v[72:73], off
	s_lshl_b32 s20, s97, 8
	s_mov_b32 s17, 0x8000
	s_ashr_i32 s21, s20, 31
	global_load_dwordx4 v[76:79], v[74:75], off
	global_load_dwordx4 v[92:95], v[204:205], off
	global_load_dwordx4 v[212:215], v[72:73], off offset:64
	global_load_dwordx4 v[68:71], v[74:75], off offset:64
	global_load_dwordx4 v[88:91], v[204:205], off offset:64
	global_load_dwordx4 v[216:219], v[72:73], off offset:512
	global_load_dwordx4 v[64:67], v[74:75], off offset:512
	global_load_dwordx4 v[80:83], v[204:205], off offset:512
	global_load_dwordx4 v[220:223], v[72:73], off offset:576
	global_load_dwordx4 v[60:63], v[74:75], off offset:576
	s_nop 0
	global_load_dwordx4 v[72:75], v[204:205], off offset:576
	v_add_u32_e32 v204, s20, v169
	v_ashrrev_i32_e32 v205, 31, v204
	v_lshlrev_b64 v[204:205], 11, v[204:205]
	v_lshl_add_u64 v[204:205], s[42:43], 0, v[204:205]
	v_lshl_add_u64 v[204:205], v[186:187], 1, v[204:205]
	global_load_dwordx2 v[240:241], v[204:205], off
	global_load_dwordx2 v[234:235], v[204:205], off offset:32
	global_load_dwordx2 v[232:233], v[204:205], off offset:256
	global_load_dwordx2 v[230:231], v[204:205], off offset:288
	s_waitcnt vmcnt(4)
	v_pk_mul_f32 v[200:201], v[210:211], 0.5 op_sel_hi:[1,0]
	v_pk_mul_f32 v[202:203], v[208:209], 0.5 op_sel_hi:[1,0]
	v_pk_mul_f32 v[196:197], v[214:215], 0.5 op_sel_hi:[1,0]
	v_pk_mul_f32 v[198:199], v[212:213], 0.5 op_sel_hi:[1,0]
	v_pk_mul_f32 v[192:193], v[218:219], 0.5 op_sel_hi:[1,0]
	v_pk_mul_f32 v[194:195], v[216:217], 0.5 op_sel_hi:[1,0]
	v_pk_mul_f32 v[188:189], v[222:223], 0.5 op_sel_hi:[1,0]
	v_pk_mul_f32 v[190:191], v[220:221], 0.5 op_sel_hi:[1,0]
	v_add_co_u32_e32 v206, vcc, s17, v204
	s_mov_b32 s17, 0x10000
	s_nop 0
	v_addc_co_u32_e32 v207, vcc, 0, v205, vcc
	global_load_dwordx2 v[228:229], v[206:207], off
	global_load_dwordx2 v[226:227], v[206:207], off offset:32
	global_load_dwordx2 v[224:225], v[206:207], off offset:256
	global_load_dwordx2 v[222:223], v[206:207], off offset:288
	v_add_co_u32_e32 v206, vcc, s17, v204
	s_mov_b32 s17, 0x18000
	s_nop 0
	v_addc_co_u32_e32 v207, vcc, 0, v205, vcc
	global_load_dwordx2 v[220:221], v[206:207], off
	global_load_dwordx2 v[218:219], v[206:207], off offset:32
	global_load_dwordx2 v[216:217], v[206:207], off offset:256
	global_load_dwordx2 v[212:213], v[206:207], off offset:288
	v_add_co_u32_e32 v206, vcc, s17, v204
	v_lshl_add_u64 v[186:187], s[20:21], 2, v[166:167]
	s_nop 0
	v_addc_co_u32_e32 v207, vcc, 0, v205, vcc
	global_load_dwordx2 v[214:215], v[206:207], off
	global_load_dwordx2 v[210:211], v[206:207], off offset:32
	global_load_dwordx2 v[208:209], v[206:207], off offset:256
	s_nop 0
	global_load_dwordx2 v[206:207], v[206:207], off offset:288
	s_waitcnt vmcnt(15)
	v_lshlrev_b32_e32 v242, 16, v240
	v_and_b32_e32 v243, 0xffff0000, v240
	v_lshlrev_b32_e32 v240, 16, v241
	v_and_b32_e32 v241, 0xffff0000, v241
	v_pk_mul_f32 v[242:243], v[92:93], v[242:243]
	v_pk_mul_f32 v[240:241], v[94:95], v[240:241]
	v_pk_fma_f32 v[156:157], v[156:157], v[202:203], v[242:243]
	v_pk_fma_f32 v[158:159], v[158:159], v[200:201], v[240:241]
	v_mul_f32_e32 v240, v157, v157
	v_fmac_f32_e32 v240, v156, v156
	v_fmac_f32_e32 v240, v158, v158
	v_fmac_f32_e32 v240, v159, v159
	v_pk_mul_f32 v[158:159], v[78:79], v[158:159]
	v_pk_mul_f32 v[156:157], v[76:77], v[156:157]
	s_nop 0
	v_cvt_pk_bf16_f32 v156, v156, v157
	v_cvt_pk_bf16_f32 v157, v158, v159
	global_store_dwordx2 v[204:205], v[156:157], off
	s_waitcnt vmcnt(15)
	v_lshlrev_b32_e32 v156, 16, v234
	v_and_b32_e32 v157, 0xffff0000, v234
	v_pk_mul_f32 v[156:157], v[88:89], v[156:157]
	v_lshlrev_b32_e32 v158, 16, v235
	v_and_b32_e32 v159, 0xffff0000, v235
	v_pk_fma_f32 v[152:153], v[152:153], v[198:199], v[156:157]
	v_pk_mul_f32 v[158:159], v[90:91], v[158:159]
	v_mul_f32_e32 v156, v153, v153
	v_pk_fma_f32 v[154:155], v[154:155], v[196:197], v[158:159]
	v_fmac_f32_e32 v156, v152, v152
	v_fmac_f32_e32 v156, v154, v154
	v_fmac_f32_e32 v156, v155, v155
	v_pk_mul_f32 v[154:155], v[70:71], v[154:155]
	v_pk_mul_f32 v[152:153], v[68:69], v[152:153]
	v_add_f32_e32 v156, v240, v156
	v_cvt_pk_bf16_f32 v152, v152, v153
	v_cvt_pk_bf16_f32 v153, v154, v155
	global_store_dwordx2 v[204:205], v[152:153], off offset:32
	s_waitcnt vmcnt(15)
	v_lshlrev_b32_e32 v152, 16, v232
	v_and_b32_e32 v153, 0xffff0000, v232
	v_pk_mul_f32 v[152:153], v[80:81], v[152:153]
	v_lshlrev_b32_e32 v154, 16, v233
	v_and_b32_e32 v155, 0xffff0000, v233
	v_pk_fma_f32 v[148:149], v[148:149], v[194:195], v[152:153]
	v_pk_mul_f32 v[154:155], v[82:83], v[154:155]
	v_mul_f32_e32 v152, v149, v149
	v_pk_fma_f32 v[150:151], v[150:151], v[192:193], v[154:155]
	v_fmac_f32_e32 v152, v148, v148
	v_fmac_f32_e32 v152, v150, v150
	v_fmac_f32_e32 v152, v151, v151
	v_pk_mul_f32 v[150:151], v[66:67], v[150:151]
	v_pk_mul_f32 v[148:149], v[64:65], v[148:149]
	v_add_f32_e32 v152, v156, v152
	v_cvt_pk_bf16_f32 v148, v148, v149
	v_cvt_pk_bf16_f32 v149, v150, v151
	global_store_dwordx2 v[204:205], v[148:149], off offset:256
	s_waitcnt vmcnt(15)
	v_lshlrev_b32_e32 v148, 16, v230
	v_and_b32_e32 v149, 0xffff0000, v230
	v_pk_mul_f32 v[148:149], v[72:73], v[148:149]
	v_lshlrev_b32_e32 v150, 16, v231
	v_and_b32_e32 v151, 0xffff0000, v231
	v_pk_fma_f32 v[144:145], v[144:145], v[190:191], v[148:149]
	v_pk_mul_f32 v[150:151], v[74:75], v[150:151]
	v_mul_f32_e32 v148, v145, v145
	v_pk_fma_f32 v[146:147], v[146:147], v[188:189], v[150:151]
	v_fmac_f32_e32 v148, v144, v144
	v_fmac_f32_e32 v148, v146, v146
	v_fmac_f32_e32 v148, v147, v147
	v_pk_mul_f32 v[146:147], v[62:63], v[146:147]
	v_pk_mul_f32 v[144:145], v[60:61], v[144:145]
	v_add_f32_e32 v148, v152, v148
	v_cvt_pk_bf16_f32 v144, v144, v145
	v_cvt_pk_bf16_f32 v145, v146, v147
	global_store_dwordx2 v[204:205], v[144:145], off offset:288
	v_mov_b32_e32 v144, v148
	s_nop 1
	v_permlane16_swap_b32_e32 v148, v144
	v_add_f32_e32 v144, v148, v144
	v_mov_b32_e32 v145, v144
	s_nop 1
	v_permlane32_swap_b32_e32 v144, v145
	s_and_saveexec_b64 s[58:59], s[4:5]
	s_cbranch_execz .LBB0_365
	v_add_f32_e32 v144, v144, v145
	global_atomic_add_f32 v[186:187], v144, off

;     __device__ __forceinline__ void operator()(const f32x4 (&acc)[2][2][4][2], const Unit& u, int wr, int wc, int fr, int fq) const {
;         const int b = (u.pm * BM) >> 11; const float cf_ = coef;
;         const int colb = u.pn * BM + wc * 32 + fq * 4;
;         f32x4 gvv[2][2], gsv[2][2], rgv[2][2];
; #pragma unroll
;         for (int bj = 0; bj < 2; ++bj)
; #pragma unroll
;             for (int n = 0; n < 2; ++n) { const f32x4 t_ = *(const f32x4*)(modp + (size_t)b * 9216 + colb + bj * HALF + n * 16); gvv[bj][n] = (f32x4){t_[0] * cf_, t_[1] * cf_, t_[2] * cf_, t_[3] * cf_};
;                 if (HAS_AN) gsv[bj][n] = *(const f32x4*)(gs + (size_t)b * 1024 + colb + bj * HALF + n * 16);
;                 if (!FROM_F32) rgv[bj][n] = *(const f32x4*)(rgs + (size_t)b * 1024 + colb + bj * HALF + n * 16); }
;         const size_t rowoff = (size_t)(u.pm * BM + wr * 64 + fr) * DM + colb;
;         const float* __restrict__ basep = xp + rowoff;
;         float* __restrict__ outp = X + rowoff;
;         bf16_t* anp = An + rowoff;
;         float* ssqp = ssq + u.pm * BM + wr * 64 + fr;
; #pragma unroll
;         for (int ai = 0; ai < 2; ++ai) {
;             f32x4 bsf[FROM_F32 ? 2 : 1][2][2]; u32x2 bsh[FROM_F32 ? 1 : 4][2][2];
;             if (!FROM_F32) {
; #pragma unroll
;                 for (int m = 0; m < 4; ++m)
; #pragma unroll
;                     for (int bj = 0; bj < 2; ++bj)
; #pragma unroll
;                         for (int n = 0; n < 2; ++n) bsh[m][bj][n] = *(const u32x2*)(anp + (size_t)(ai * HALF + m * 16) * DM + bj * HALF + n * 16);
;             }
; #pragma unroll
;             for (int mp = 0; mp < 2; ++mp) {
;                 if (FROM_F32) {
; #pragma unroll
;                     for (int mm = 0; mm < 2; ++mm)
; #pragma unroll
;                         for (int bj = 0; bj < 2; ++bj)
; #pragma unroll
;                             for (int n = 0; n < 2; ++n) bsf[mm][bj][n] = *(const f32x4*)(basep + (size_t)(ai * HALF + (2 * mp + mm) * 16) * DM + bj * HALF + n * 16);
;                 }
; #pragma unroll
;                 for (int mm = 0; mm < 2; ++mm) {
;                     const int m = 2 * mp + mm; const size_t ro = (size_t)(ai * HALF + m * 16) * DM; float sq = 0.f;
; #pragma unroll
;                     for (int bj = 0; bj < 2; ++bj)
; #pragma unroll
;                         for (int n = 0; n < 2; ++n) {
.LBB0_1092:
	s_ashr_i32 s46, s81, 3
	v_lshl_or_b32 v170, s82, 8, v247
	s_ashr_i32 s47, s46, 31
	s_mul_i32 s58, s46, 0x9000
	s_mul_hi_i32 s59, s46, 0x9000
	s_add_u32 s58, s22, s58
	v_ashrrev_i32_e32 v171, 31, v170
	s_addc_u32 s59, s23, s59
	v_lshlrev_b64 v[60:61], 2, v[170:171]
	s_lshl_b64 s[46:47], s[46:47], 12
	v_lshl_add_u64 v[72:73], s[58:59], 0, v[60:61]
	s_add_u32 s58, s34, s46
	s_addc_u32 s59, s35, s47
	s_add_u32 s46, s36, s46
	s_addc_u32 s47, s37, s47
	v_lshl_add_u64 v[74:75], s[58:59], 0, v[60:61]
	v_lshl_add_u64 v[206:207], s[46:47], 0, v[60:61]
	global_load_dwordx4 v[208:211], v[72:73], off
	s_lshl_b32 s46, s81, 8
	s_ashr_i32 s47, s46, 31
	global_load_dwordx4 v[76:79], v[74:75], off
	global_load_dwordx4 v[92:95], v[206:207], off
	global_load_dwordx4 v[212:215], v[72:73], off offset:64
	global_load_dwordx4 v[68:71], v[74:75], off offset:64
	global_load_dwordx4 v[88:91], v[206:207], off offset:64
	global_load_dwordx4 v[216:219], v[72:73], off offset:512
	global_load_dwordx4 v[64:67], v[74:75], off offset:512
	global_load_dwordx4 v[80:83], v[206:207], off offset:512
	global_load_dwordx4 v[220:223], v[72:73], off offset:576
	global_load_dwordx4 v[60:63], v[74:75], off offset:576
	s_nop 0
	global_load_dwordx4 v[72:75], v[206:207], off offset:576
	v_add_u32_e32 v206, s46, v185
	v_ashrrev_i32_e32 v207, 31, v206
	v_lshlrev_b64 v[206:207], 11, v[206:207]
	v_lshl_add_u64 v[206:207], s[42:43], 0, v[206:207]
	v_lshl_add_u64 v[206:207], v[170:171], 1, v[206:207]
	global_load_dwordx2 v[240:241], v[206:207], off
	global_load_dwordx2 v[236:237], v[206:207], off offset:32
	global_load_dwordx2 v[234:235], v[206:207], off offset:256
	global_load_dwordx2 v[232:233], v[206:207], off offset:288
	s_waitcnt vmcnt(4)
	v_pk_mul_f32 v[202:203], v[210:211], 0.5 op_sel_hi:[1,0]
	v_pk_mul_f32 v[204:205], v[208:209], 0.5 op_sel_hi:[1,0]
	v_pk_mul_f32 v[198:199], v[214:215], 0.5 op_sel_hi:[1,0]
	v_pk_mul_f32 v[200:201], v[212:213], 0.5 op_sel_hi:[1,0]
	v_pk_mul_f32 v[194:195], v[218:219], 0.5 op_sel_hi:[1,0]
	v_pk_mul_f32 v[196:197], v[216:217], 0.5 op_sel_hi:[1,0]
	v_pk_mul_f32 v[172:173], v[222:223], 0.5 op_sel_hi:[1,0]
	v_pk_mul_f32 v[174:175], v[220:221], 0.5 op_sel_hi:[1,0]
	v_lshl_add_u64 v[170:171], s[46:47], 2, v[164:165]
	s_mov_b32 s46, 0x8000
	v_add_co_u32_e32 v208, vcc, s46, v206
	s_mov_b32 s46, 0x10000
	s_nop 0
	v_addc_co_u32_e32 v209, vcc, 0, v207, vcc
	global_load_dwordx2 v[230:231], v[208:209], off
	global_load_dwordx2 v[228:229], v[208:209], off offset:32
	global_load_dwordx2 v[226:227], v[208:209], off offset:256
	global_load_dwordx2 v[224:225], v[208:209], off offset:288
	v_add_co_u32_e32 v208, vcc, s46, v206
	s_mov_b32 s46, 0x18000
	s_nop 0
	v_addc_co_u32_e32 v209, vcc, 0, v207, vcc
	global_load_dwordx2 v[222:223], v[208:209], off
	global_load_dwordx2 v[220:221], v[208:209], off offset:32
	global_load_dwordx2 v[218:219], v[208:209], off offset:256
	global_load_dwordx2 v[214:215], v[208:209], off offset:288
	v_add_co_u32_e32 v208, vcc, s46, v206
	s_waitcnt vmcnt(11)
	v_lshlrev_b32_e32 v242, 16, v240
	v_addc_co_u32_e32 v209, vcc, 0, v207, vcc
	global_load_dwordx2 v[216:217], v[208:209], off
	global_load_dwordx2 v[212:213], v[208:209], off offset:32
	global_load_dwordx2 v[210:211], v[208:209], off offset:256
	s_nop 0
	global_load_dwordx2 v[208:209], v[208:209], off offset:288
	v_and_b32_e32 v243, 0xffff0000, v240
	v_lshlrev_b32_e32 v240, 16, v241
	v_and_b32_e32 v241, 0xffff0000, v241
	v_pk_mul_f32 v[242:243], v[92:93], v[242:243]
	v_pk_mul_f32 v[240:241], v[94:95], v[240:241]
	v_pk_fma_f32 v[156:157], v[156:157], v[204:205], v[242:243]
	v_pk_fma_f32 v[158:159], v[158:159], v[202:203], v[240:241]
	v_mul_f32_e32 v240, v157, v157
	v_fmac_f32_e32 v240, v156, v156
	v_fmac_f32_e32 v240, v158, v158
	v_fmac_f32_e32 v240, v159, v159
	v_pk_mul_f32 v[158:159], v[78:79], v[158:159]
	v_pk_mul_f32 v[156:157], v[76:77], v[156:157]
	s_nop 0
	v_cvt_pk_bf16_f32 v156, v156, v157
	v_cvt_pk_bf16_f32 v157, v158, v159
	global_store_dwordx2 v[206:207], v[156:157], off
	s_waitcnt vmcnt(15)
	v_lshlrev_b32_e32 v156, 16, v236
	v_and_b32_e32 v157, 0xffff0000, v236
	v_pk_mul_f32 v[156:157], v[88:89], v[156:157]
	v_lshlrev_b32_e32 v158, 16, v237
	v_and_b32_e32 v159, 0xffff0000, v237
	v_pk_fma_f32 v[152:153], v[152:153], v[200:201], v[156:157]
	v_pk_mul_f32 v[158:159], v[90:91], v[158:159]
	v_mul_f32_e32 v156, v153, v153
	v_pk_fma_f32 v[154:155], v[154:155], v[198:199], v[158:159]
	v_fmac_f32_e32 v156, v152, v152
	v_fmac_f32_e32 v156, v154, v154
	v_fmac_f32_e32 v156, v155, v155
	v_pk_mul_f32 v[154:155], v[70:71], v[154:155]
	v_pk_mul_f32 v[152:153], v[68:69], v[152:153]
	v_add_f32_e32 v156, v240, v156
	v_cvt_pk_bf16_f32 v152, v152, v153
	v_cvt_pk_bf16_f32 v153, v154, v155
	global_store_dwordx2 v[206:207], v[152:153], off offset:32
	s_waitcnt vmcnt(15)
	v_lshlrev_b32_e32 v152, 16, v234
	v_and_b32_e32 v153, 0xffff0000, v234
	v_pk_mul_f32 v[152:153], v[80:81], v[152:153]
	v_lshlrev_b32_e32 v154, 16, v235
	v_and_b32_e32 v155, 0xffff0000, v235
	v_pk_fma_f32 v[148:149], v[148:149], v[196:197], v[152:153]
	v_pk_mul_f32 v[154:155], v[82:83], v[154:155]
	v_mul_f32_e32 v152, v149, v149
	v_pk_fma_f32 v[150:151], v[150:151], v[194:195], v[154:155]
	v_fmac_f32_e32 v152, v148, v148
	v_fmac_f32_e32 v152, v150, v150
	v_fmac_f32_e32 v152, v151, v151
	v_pk_mul_f32 v[150:151], v[66:67], v[150:151]
	v_pk_mul_f32 v[148:149], v[64:65], v[148:149]
	v_add_f32_e32 v152, v156, v152
	v_cvt_pk_bf16_f32 v148, v148, v149
	v_cvt_pk_bf16_f32 v149, v150, v151
	global_store_dwordx2 v[206:207], v[148:149], off offset:256
	s_waitcnt vmcnt(15)
	v_lshlrev_b32_e32 v148, 16, v232
	v_and_b32_e32 v149, 0xffff0000, v232
	v_pk_mul_f32 v[148:149], v[72:73], v[148:149]
	v_lshlrev_b32_e32 v150, 16, v233
	v_and_b32_e32 v151, 0xffff0000, v233
	v_pk_fma_f32 v[144:145], v[144:145], v[174:175], v[148:149]
	v_pk_mul_f32 v[150:151], v[74:75], v[150:151]
	v_mul_f32_e32 v148, v145, v145
	v_pk_fma_f32 v[146:147], v[146:147], v[172:173], v[150:151]
	v_fmac_f32_e32 v148, v144, v144
	v_fmac_f32_e32 v148, v146, v146
	v_fmac_f32_e32 v148, v147, v147
	v_pk_mul_f32 v[146:147], v[62:63], v[146:147]
	v_pk_mul_f32 v[144:145], v[60:61], v[144:145]
	v_add_f32_e32 v148, v152, v148
	v_cvt_pk_bf16_f32 v144, v144, v145
	v_cvt_pk_bf16_f32 v145, v146, v147
	global_store_dwordx2 v[206:207], v[144:145], off offset:288
	v_mov_b32_e32 v144, v148
	s_nop 1
	v_permlane16_swap_b32_e32 v148, v144
	v_add_f32_e32 v144, v148, v144
	v_mov_b32_e32 v145, v144
	s_nop 1
	v_permlane32_swap_b32_e32 v144, v145
	s_and_saveexec_b64 s[58:59], s[12:13]
	s_cbranch_execz .LBB0_1094
	v_add_f32_e32 v144, v144, v145
	global_atomic_add_f32 v[170:171], v144, off
